# hand-written P0 rmsnorm/forget-gate row loop: wf weights hoisted to VGPRs, 2-row prefetch, transposed 8-way lane reduction
# speedup vs baseline: 1.0125x; 1.0125x over previous
.LBB0_286:
	s_or_b64 exec, exec, s[4:5]
	s_cmp_lt_i32 s0, 0x8000
	s_waitcnt lgkmcnt(0)
	s_barrier
	s_cbranch_scc0 .LBB0_295
	v_mbcnt_lo_u32_b32 v1, -1, 0
	v_mbcnt_hi_u32_b32 v1, -1, v1
	v_readlane_b32 s10, v255, 2
	v_readlane_b32 s11, v255, 3
	v_readlane_b32 s8, v255, 4
	v_readlane_b32 s9, v255, 5
	v_readlane_b32 s4, v255, 8
	v_readlane_b32 s5, v255, 9
	v_lshlrev_b32_e32 v2, 3, v1
	v_bfe_u32 v6, v1, 5, 1
	v_bfe_u32 v7, v1, 2, 1
	v_bfe_u32 v8, v1, 3, 1
	v_lshlrev_b32_e32 v6, 2, v6
	v_lshl_or_b32 v6, v7, 1, v6
	v_or_b32_e32 v6, v6, v8
	v_lshlrev_b32_e32 v4, 2, v6
	v_lshlrev_b32_e32 v1, 4, v1
	v_mov_b32_e32 v0, 0
	v_mov_b32_e32 v153, 0x358637bd
	s_lshl_b32 s53, s96, 11
	s_lshl_b32 s54, s96, 2
	s_lshl_b32 s55, s96, 5
	s_lshl_b32 s59, s96, 1
	s_movk_i32 s61, 0x7fff
	s_mov_b32 s57, 0x3fb8aa3b
	s_mov_b32 s62, 0x00001111
	s_mov_b32 s63, 0x00001111
	s_mov_b32 s64, 0xff00ff00
	s_mov_b32 s65, 0xff00ff00
	s_mov_b32 s66, 0xf0f0f0f0
	s_mov_b32 s67, 0xf0f0f0f0
	global_load_dwordx4 v[64:67], v1, s[8:9]
	global_load_dwordx4 v[68:71], v1, s[8:9] offset:1024
	global_load_dwordx4 v[72:75], v1, s[8:9] offset:2048
	global_load_dwordx4 v[76:79], v1, s[8:9] offset:3072
	global_load_dword v156, v4, s[4:5]
	s_lshl_b32 s1, s0, 11
	s_add_u32 s12, s30, s1
	s_addc_u32 s13, s31, 0
	s_add_u32 s12, s12, 0x2400000
	s_addc_u32 s13, s13, 0
	s_lshl_b32 s1, s0, 2
	s_add_u32 s14, s30, s1
	s_addc_u32 s15, s31, 0
	s_add_u32 s14, s14, 0x4d0000
	s_addc_u32 s15, s15, 0
	s_lshl_b32 s1, s0, 5
	s_add_u32 s26, s30, s1
	s_addc_u32 s27, s31, 0
	s_add_u32 s26, s26, 0x2200000
	s_addc_u32 s27, s27, 0
	s_lshl_b32 s4, s0, 12
	s_add_u32 s4, s10, s4
	s_addc_u32 s5, s11, 0
	global_load_dwordx4 v[16:19], v1, s[4:5]
	global_load_dwordx4 v[20:23], v1, s[4:5] offset:1024
	global_load_dwordx4 v[24:27], v1, s[4:5] offset:2048
	global_load_dwordx4 v[28:31], v1, s[4:5] offset:3072
	s_add_i32 s1, s0, s96
	s_min_i32 s1, s1, s61
	s_lshl_b32 s4, s1, 12
	s_add_u32 s4, s10, s4
	s_addc_u32 s5, s11, 0
	global_load_dwordx4 v[32:35], v1, s[4:5]
	global_load_dwordx4 v[36:39], v1, s[4:5] offset:1024
	global_load_dwordx4 v[40:43], v1, s[4:5] offset:2048
	global_load_dwordx4 v[44:47], v1, s[4:5] offset:3072
	ds_read_b128 v[80:83], v1
	ds_read_b128 v[84:87], v1 offset:1024
	ds_read_b128 v[88:91], v1 offset:2048
	ds_read_b128 v[92:95], v1 offset:3072
	ds_read_b128 v[96:99], v1 offset:4096
	ds_read_b128 v[100:103], v1 offset:5120
	ds_read_b128 v[104:107], v1 offset:6144
	ds_read_b128 v[108:111], v1 offset:7168
	ds_read_b128 v[112:115], v1 offset:8192
	ds_read_b128 v[116:119], v1 offset:9216
	ds_read_b128 v[120:123], v1 offset:10240
	ds_read_b128 v[124:127], v1 offset:11264
	ds_read_b128 v[128:131], v1 offset:12288
	ds_read_b128 v[132:135], v1 offset:13312
	ds_read_b128 v[136:139], v1 offset:14336
	ds_read_b128 v[140:143], v1 offset:15360
	ds_read_b128 v[176:179], v1 offset:16384
	ds_read_b128 v[180:183], v1 offset:17408
	ds_read_b128 v[184:187], v1 offset:18432
	ds_read_b128 v[188:191], v1 offset:19456
	ds_read_b128 v[192:195], v1 offset:20480
	ds_read_b128 v[196:199], v1 offset:21504
	ds_read_b128 v[200:203], v1 offset:22528
	ds_read_b128 v[204:207], v1 offset:23552
	ds_read_b128 v[208:211], v1 offset:24576
	ds_read_b128 v[212:215], v1 offset:25600
	ds_read_b128 v[216:219], v1 offset:26624
	ds_read_b128 v[220:223], v1 offset:27648
	ds_read_b128 v[224:227], v1 offset:28672
	ds_read_b128 v[228:231], v1 offset:29696
	ds_read_b128 v[232:235], v1 offset:30720
	ds_read_b128 v[236:239], v1 offset:31744
	s_waitcnt vmcnt(0) lgkmcnt(0)
.Lrow_loop:
	s_add_i32 s1, s0, s59
	s_min_i32 s1, s1, s61
	s_lshl_b32 s4, s1, 12
	s_add_u32 s4, s10, s4
	s_addc_u32 s5, s11, 0
	global_load_dwordx4 v[48:51], v1, s[4:5]
	global_load_dwordx4 v[52:55], v1, s[4:5] offset:1024
	global_load_dwordx4 v[56:59], v1, s[4:5] offset:2048
	global_load_dwordx4 v[60:63], v1, s[4:5] offset:3072
	s_waitcnt vmcnt(20)
	v_pk_mul_f32 v[150:151], v[16:17], v[16:17]
	v_pk_fma_f32 v[150:151], v[18:19], v[18:19], v[150:151]
	v_pk_fma_f32 v[150:151], v[20:21], v[20:21], v[150:151]
	v_pk_fma_f32 v[150:151], v[22:23], v[22:23], v[150:151]
	v_pk_fma_f32 v[150:151], v[24:25], v[24:25], v[150:151]
	v_pk_fma_f32 v[150:151], v[26:27], v[26:27], v[150:151]
	v_pk_fma_f32 v[150:151], v[28:29], v[28:29], v[150:151]
	v_pk_fma_f32 v[150:151], v[30:31], v[30:31], v[150:151]
	v_add_f32_e32 v150, v150, v151
	s_nop 1
	v_add_f32_dpp v150, v150, v150 quad_perm:[1,0,3,2] row_mask:0xf bank_mask:0xf bound_ctrl:1
	s_nop 1
	v_add_f32_dpp v150, v150, v150 quad_perm:[2,3,0,1] row_mask:0xf bank_mask:0xf bound_ctrl:1
	s_nop 1
	v_add_f32_dpp v150, v150, v150 row_half_mirror row_mask:0xf bank_mask:0xf bound_ctrl:1
	s_nop 1
	v_add_f32_dpp v150, v150, v150 row_mirror row_mask:0xf bank_mask:0xf bound_ctrl:1
	s_nop 1
	v_readlane_b32 s7, v150, 0
	v_readlane_b32 s8, v150, 16
	v_readlane_b32 s9, v150, 32
	v_readlane_b32 s18, v150, 48
	s_nop 1
	v_mov_b32_e32 v150, s7
	v_add_f32_e32 v150, s8, v150
	v_add_f32_e32 v150, s9, v150
	v_add_f32_e32 v150, s18, v150
	v_fmamk_f32 v150, v150, 0x3a800000, v153
	v_sqrt_f32_e32 v152, v150
	s_nop 0
	v_rcp_f32_e32 v154, v152
	s_mov_b64 exec, 1
	global_store_dword v0, v152, s[14:15]
	s_mov_b64 exec, -1
	v_pk_mul_f32 v[16:17], v[16:17], v[154:155] op_sel_hi:[1,0]
	v_pk_mul_f32 v[18:19], v[18:19], v[154:155] op_sel_hi:[1,0]
	v_pk_mul_f32 v[20:21], v[20:21], v[154:155] op_sel_hi:[1,0]
	v_pk_mul_f32 v[22:23], v[22:23], v[154:155] op_sel_hi:[1,0]
	v_pk_mul_f32 v[24:25], v[24:25], v[154:155] op_sel_hi:[1,0]
	v_pk_mul_f32 v[26:27], v[26:27], v[154:155] op_sel_hi:[1,0]
	v_pk_mul_f32 v[28:29], v[28:29], v[154:155] op_sel_hi:[1,0]
	v_pk_mul_f32 v[30:31], v[30:31], v[154:155] op_sel_hi:[1,0]
	v_pk_mul_f32 v[16:17], v[16:17], v[64:65]
	v_pk_mul_f32 v[18:19], v[18:19], v[66:67]
	v_pk_mul_f32 v[20:21], v[20:21], v[68:69]
	v_pk_mul_f32 v[22:23], v[22:23], v[70:71]
	v_pk_mul_f32 v[24:25], v[24:25], v[72:73]
	v_pk_mul_f32 v[26:27], v[26:27], v[74:75]
	v_pk_mul_f32 v[28:29], v[28:29], v[76:77]
	v_pk_mul_f32 v[30:31], v[30:31], v[78:79]
	v_cvt_pk_bf16_f32 v240, v16, v17
	v_cvt_pk_bf16_f32 v241, v18, v19
	v_cvt_pk_bf16_f32 v242, v20, v21
	v_cvt_pk_bf16_f32 v243, v22, v23
	v_cvt_pk_bf16_f32 v244, v24, v25
	v_cvt_pk_bf16_f32 v245, v26, v27
	v_cvt_pk_bf16_f32 v246, v28, v29
	v_cvt_pk_bf16_f32 v247, v30, v31
	global_store_dwordx2 v2, v[240:241], s[12:13]
	global_store_dwordx2 v2, v[242:243], s[12:13] offset:512
	global_store_dwordx2 v2, v[244:245], s[12:13] offset:1024
	global_store_dwordx2 v2, v[246:247], s[12:13] offset:1536
	v_pk_mul_f32 v[6:7], v[16:17], v[80:81]
	v_pk_mul_f32 v[8:9], v[16:17], v[96:97]
	v_pk_mul_f32 v[10:11], v[16:17], v[112:113]
	v_pk_mul_f32 v[12:13], v[16:17], v[128:129]
	v_pk_mul_f32 v[14:15], v[16:17], v[176:177]
	v_pk_mul_f32 v[144:145], v[16:17], v[192:193]
	v_pk_mul_f32 v[146:147], v[16:17], v[208:209]
	v_pk_mul_f32 v[148:149], v[16:17], v[224:225]
	v_pk_fma_f32 v[6:7], v[18:19], v[82:83], v[6:7]
	v_pk_fma_f32 v[8:9], v[18:19], v[98:99], v[8:9]
	v_pk_fma_f32 v[10:11], v[18:19], v[114:115], v[10:11]
	v_pk_fma_f32 v[12:13], v[18:19], v[130:131], v[12:13]
	v_pk_fma_f32 v[14:15], v[18:19], v[178:179], v[14:15]
	v_pk_fma_f32 v[144:145], v[18:19], v[194:195], v[144:145]
	v_pk_fma_f32 v[146:147], v[18:19], v[210:211], v[146:147]
	v_pk_fma_f32 v[148:149], v[18:19], v[226:227], v[148:149]
	v_pk_fma_f32 v[6:7], v[20:21], v[84:85], v[6:7]
	v_pk_fma_f32 v[8:9], v[20:21], v[100:101], v[8:9]
	v_pk_fma_f32 v[10:11], v[20:21], v[116:117], v[10:11]
	v_pk_fma_f32 v[12:13], v[20:21], v[132:133], v[12:13]
	v_pk_fma_f32 v[14:15], v[20:21], v[180:181], v[14:15]
	v_pk_fma_f32 v[144:145], v[20:21], v[196:197], v[144:145]
	v_pk_fma_f32 v[146:147], v[20:21], v[212:213], v[146:147]
	v_pk_fma_f32 v[148:149], v[20:21], v[228:229], v[148:149]
	v_pk_fma_f32 v[6:7], v[22:23], v[86:87], v[6:7]
	v_pk_fma_f32 v[8:9], v[22:23], v[102:103], v[8:9]
	v_pk_fma_f32 v[10:11], v[22:23], v[118:119], v[10:11]
	v_pk_fma_f32 v[12:13], v[22:23], v[134:135], v[12:13]
	v_pk_fma_f32 v[14:15], v[22:23], v[182:183], v[14:15]
	v_pk_fma_f32 v[144:145], v[22:23], v[198:199], v[144:145]
	v_pk_fma_f32 v[146:147], v[22:23], v[214:215], v[146:147]
	v_pk_fma_f32 v[148:149], v[22:23], v[230:231], v[148:149]
	v_pk_fma_f32 v[6:7], v[24:25], v[88:89], v[6:7]
	v_pk_fma_f32 v[8:9], v[24:25], v[104:105], v[8:9]
	v_pk_fma_f32 v[10:11], v[24:25], v[120:121], v[10:11]
	v_pk_fma_f32 v[12:13], v[24:25], v[136:137], v[12:13]
	v_pk_fma_f32 v[14:15], v[24:25], v[184:185], v[14:15]
	v_pk_fma_f32 v[144:145], v[24:25], v[200:201], v[144:145]
	v_pk_fma_f32 v[146:147], v[24:25], v[216:217], v[146:147]
	v_pk_fma_f32 v[148:149], v[24:25], v[232:233], v[148:149]
	v_pk_fma_f32 v[6:7], v[26:27], v[90:91], v[6:7]
	v_pk_fma_f32 v[8:9], v[26:27], v[106:107], v[8:9]
	v_pk_fma_f32 v[10:11], v[26:27], v[122:123], v[10:11]
	v_pk_fma_f32 v[12:13], v[26:27], v[138:139], v[12:13]
	v_pk_fma_f32 v[14:15], v[26:27], v[186:187], v[14:15]
	v_pk_fma_f32 v[144:145], v[26:27], v[202:203], v[144:145]
	v_pk_fma_f32 v[146:147], v[26:27], v[218:219], v[146:147]
	v_pk_fma_f32 v[148:149], v[26:27], v[234:235], v[148:149]
	v_pk_fma_f32 v[6:7], v[28:29], v[92:93], v[6:7]
	v_pk_fma_f32 v[8:9], v[28:29], v[108:109], v[8:9]
	v_pk_fma_f32 v[10:11], v[28:29], v[124:125], v[10:11]
	v_pk_fma_f32 v[12:13], v[28:29], v[140:141], v[12:13]
	v_pk_fma_f32 v[14:15], v[28:29], v[188:189], v[14:15]
	v_pk_fma_f32 v[144:145], v[28:29], v[204:205], v[144:145]
	v_pk_fma_f32 v[146:147], v[28:29], v[220:221], v[146:147]
	v_pk_fma_f32 v[148:149], v[28:29], v[236:237], v[148:149]
	v_pk_fma_f32 v[6:7], v[30:31], v[94:95], v[6:7]
	v_pk_fma_f32 v[8:9], v[30:31], v[110:111], v[8:9]
	v_pk_fma_f32 v[10:11], v[30:31], v[126:127], v[10:11]
	v_pk_fma_f32 v[12:13], v[30:31], v[142:143], v[12:13]
	v_pk_fma_f32 v[14:15], v[30:31], v[190:191], v[14:15]
	v_pk_fma_f32 v[144:145], v[30:31], v[206:207], v[144:145]
	v_pk_fma_f32 v[146:147], v[30:31], v[222:223], v[146:147]
	v_pk_fma_f32 v[148:149], v[30:31], v[238:239], v[148:149]
	v_add_f32_e32 v6, v6, v7
	v_add_f32_e32 v8, v8, v9
	v_add_f32_e32 v10, v10, v11
	v_add_f32_e32 v12, v12, v13
	v_add_f32_e32 v14, v14, v15
	v_add_f32_e32 v144, v144, v145
	v_add_f32_e32 v146, v146, v147
	v_add_f32_e32 v148, v148, v149
	s_nop 1
	v_permlane32_swap_b32_e32 v6, v14
	v_permlane32_swap_b32_e32 v8, v144
	v_permlane32_swap_b32_e32 v10, v146
	v_permlane32_swap_b32_e32 v12, v148
	v_add_f32_e32 v6, v6, v14
	v_add_f32_e32 v8, v8, v144
	v_add_f32_e32 v10, v10, v146
	v_add_f32_e32 v12, v12, v148
	s_nop 1
	v_add_f32_dpp v14, v6, v6 row_ror:8 row_mask:0xf bank_mask:0xf bound_ctrl:1
	v_add_f32_dpp v144, v8, v8 row_ror:8 row_mask:0xf bank_mask:0xf bound_ctrl:1
	v_add_f32_dpp v146, v10, v10 row_ror:8 row_mask:0xf bank_mask:0xf bound_ctrl:1
	v_add_f32_dpp v148, v12, v12 row_ror:8 row_mask:0xf bank_mask:0xf bound_ctrl:1
	v_cndmask_b32_e64 v6, v14, v144, s[64:65]
	v_cndmask_b32_e64 v8, v146, v148, s[64:65]
	s_nop 1
	v_add_f32_dpp v10, v6, v6 row_half_mirror row_mask:0xf bank_mask:0xf bound_ctrl:1
	v_add_f32_dpp v12, v8, v8 row_half_mirror row_mask:0xf bank_mask:0xf bound_ctrl:1
	v_cndmask_b32_e64 v6, v10, v12, s[66:67]
	s_nop 1
	v_add_f32_dpp v6, v6, v6 quad_perm:[1,0,3,2] row_mask:0xf bank_mask:0xf bound_ctrl:1
	s_nop 1
	v_add_f32_dpp v6, v6, v6 quad_perm:[2,3,0,1] row_mask:0xf bank_mask:0xf bound_ctrl:1
	s_nop 0
	ds_swizzle_b32 v254, v6 offset:0x401f
	s_waitcnt lgkmcnt(0)
	v_add_f32_e32 v248, v6, v254
	v_add_f32_e32 v248, v248, v156
	v_mul_f32_e64 v249, -|v248|, s57
	v_exp_f32_e32 v249, v249
	v_min_f32_e32 v253, 0, v248
	v_add_f32_e32 v250, 1.0, v249
	v_log_f32_e32 v251, v250
	v_add_f32_e32 v252, -1.0, v250
	v_rcp_f32_e32 v250, v252
	v_cmp_eq_f32_e32 vcc, 0, v252
	v_mul_f32_e32 v251, 0x3f317218, v251
	v_mul_f32_e32 v251, v251, v249
	v_mul_f32_e32 v251, v251, v250
	v_cndmask_b32_e32 v251, v251, v249, vcc
	v_sub_f32_e32 v253, v253, v251
	s_mov_b64 exec, s[62:63]
	global_store_dword v4, v253, s[26:27]
	s_mov_b64 exec, -1
	s_add_u32 s12, s12, s53
	s_addc_u32 s13, s13, 0
	s_add_u32 s14, s14, s54
	s_addc_u32 s15, s15, 0
	s_add_u32 s26, s26, s55
	s_addc_u32 s27, s27, 0
	s_add_i32 s0, s0, s96
	s_cmp_lt_i32 s0, 0x8000
	s_cbranch_scc0 .Lrow_done
	s_add_i32 s1, s0, s59
	s_min_i32 s1, s1, s61
	s_lshl_b32 s4, s1, 12
	s_add_u32 s4, s10, s4
	s_addc_u32 s5, s11, 0
	global_load_dwordx4 v[16:19], v1, s[4:5]
	global_load_dwordx4 v[20:23], v1, s[4:5] offset:1024
	global_load_dwordx4 v[24:27], v1, s[4:5] offset:2048
	global_load_dwordx4 v[28:31], v1, s[4:5] offset:3072
	s_waitcnt vmcnt(20)
	v_pk_mul_f32 v[150:151], v[32:33], v[32:33]
	v_pk_fma_f32 v[150:151], v[34:35], v[34:35], v[150:151]
	v_pk_fma_f32 v[150:151], v[36:37], v[36:37], v[150:151]
	v_pk_fma_f32 v[150:151], v[38:39], v[38:39], v[150:151]
	v_pk_fma_f32 v[150:151], v[40:41], v[40:41], v[150:151]
	v_pk_fma_f32 v[150:151], v[42:43], v[42:43], v[150:151]
	v_pk_fma_f32 v[150:151], v[44:45], v[44:45], v[150:151]
	v_pk_fma_f32 v[150:151], v[46:47], v[46:47], v[150:151]
	v_add_f32_e32 v150, v150, v151
	s_nop 1
	v_add_f32_dpp v150, v150, v150 quad_perm:[1,0,3,2] row_mask:0xf bank_mask:0xf bound_ctrl:1
	s_nop 1
	v_add_f32_dpp v150, v150, v150 quad_perm:[2,3,0,1] row_mask:0xf bank_mask:0xf bound_ctrl:1
	s_nop 1
	v_add_f32_dpp v150, v150, v150 row_half_mirror row_mask:0xf bank_mask:0xf bound_ctrl:1
	s_nop 1
	v_add_f32_dpp v150, v150, v150 row_mirror row_mask:0xf bank_mask:0xf bound_ctrl:1
	s_nop 1
	v_readlane_b32 s7, v150, 0
	v_readlane_b32 s8, v150, 16
	v_readlane_b32 s9, v150, 32
	v_readlane_b32 s18, v150, 48
	s_nop 1
	v_mov_b32_e32 v150, s7
	v_add_f32_e32 v150, s8, v150
	v_add_f32_e32 v150, s9, v150
	v_add_f32_e32 v150, s18, v150
	v_fmamk_f32 v150, v150, 0x3a800000, v153
	v_sqrt_f32_e32 v152, v150
	s_nop 0
	v_rcp_f32_e32 v154, v152
	s_mov_b64 exec, 1
	global_store_dword v0, v152, s[14:15]
	s_mov_b64 exec, -1
	v_pk_mul_f32 v[32:33], v[32:33], v[154:155] op_sel_hi:[1,0]
	v_pk_mul_f32 v[34:35], v[34:35], v[154:155] op_sel_hi:[1,0]
	v_pk_mul_f32 v[36:37], v[36:37], v[154:155] op_sel_hi:[1,0]
	v_pk_mul_f32 v[38:39], v[38:39], v[154:155] op_sel_hi:[1,0]
	v_pk_mul_f32 v[40:41], v[40:41], v[154:155] op_sel_hi:[1,0]
	v_pk_mul_f32 v[42:43], v[42:43], v[154:155] op_sel_hi:[1,0]
	v_pk_mul_f32 v[44:45], v[44:45], v[154:155] op_sel_hi:[1,0]
	v_pk_mul_f32 v[46:47], v[46:47], v[154:155] op_sel_hi:[1,0]
	v_pk_mul_f32 v[32:33], v[32:33], v[64:65]
	v_pk_mul_f32 v[34:35], v[34:35], v[66:67]
	v_pk_mul_f32 v[36:37], v[36:37], v[68:69]
	v_pk_mul_f32 v[38:39], v[38:39], v[70:71]
	v_pk_mul_f32 v[40:41], v[40:41], v[72:73]
	v_pk_mul_f32 v[42:43], v[42:43], v[74:75]
	v_pk_mul_f32 v[44:45], v[44:45], v[76:77]
	v_pk_mul_f32 v[46:47], v[46:47], v[78:79]
	v_cvt_pk_bf16_f32 v240, v32, v33
	v_cvt_pk_bf16_f32 v241, v34, v35
	v_cvt_pk_bf16_f32 v242, v36, v37
	v_cvt_pk_bf16_f32 v243, v38, v39
	v_cvt_pk_bf16_f32 v244, v40, v41
	v_cvt_pk_bf16_f32 v245, v42, v43
	v_cvt_pk_bf16_f32 v246, v44, v45
	v_cvt_pk_bf16_f32 v247, v46, v47
	global_store_dwordx2 v2, v[240:241], s[12:13]
	global_store_dwordx2 v2, v[242:243], s[12:13] offset:512
	global_store_dwordx2 v2, v[244:245], s[12:13] offset:1024
	global_store_dwordx2 v2, v[246:247], s[12:13] offset:1536
	v_pk_mul_f32 v[6:7], v[32:33], v[80:81]
	v_pk_mul_f32 v[8:9], v[32:33], v[96:97]
	v_pk_mul_f32 v[10:11], v[32:33], v[112:113]
	v_pk_mul_f32 v[12:13], v[32:33], v[128:129]
	v_pk_mul_f32 v[14:15], v[32:33], v[176:177]
	v_pk_mul_f32 v[144:145], v[32:33], v[192:193]
	v_pk_mul_f32 v[146:147], v[32:33], v[208:209]
	v_pk_mul_f32 v[148:149], v[32:33], v[224:225]
	v_pk_fma_f32 v[6:7], v[34:35], v[82:83], v[6:7]
	v_pk_fma_f32 v[8:9], v[34:35], v[98:99], v[8:9]
	v_pk_fma_f32 v[10:11], v[34:35], v[114:115], v[10:11]
	v_pk_fma_f32 v[12:13], v[34:35], v[130:131], v[12:13]
	v_pk_fma_f32 v[14:15], v[34:35], v[178:179], v[14:15]
	v_pk_fma_f32 v[144:145], v[34:35], v[194:195], v[144:145]
	v_pk_fma_f32 v[146:147], v[34:35], v[210:211], v[146:147]
	v_pk_fma_f32 v[148:149], v[34:35], v[226:227], v[148:149]
	v_pk_fma_f32 v[6:7], v[36:37], v[84:85], v[6:7]
	v_pk_fma_f32 v[8:9], v[36:37], v[100:101], v[8:9]
	v_pk_fma_f32 v[10:11], v[36:37], v[116:117], v[10:11]
	v_pk_fma_f32 v[12:13], v[36:37], v[132:133], v[12:13]
	v_pk_fma_f32 v[14:15], v[36:37], v[180:181], v[14:15]
	v_pk_fma_f32 v[144:145], v[36:37], v[196:197], v[144:145]
	v_pk_fma_f32 v[146:147], v[36:37], v[212:213], v[146:147]
	v_pk_fma_f32 v[148:149], v[36:37], v[228:229], v[148:149]
	v_pk_fma_f32 v[6:7], v[38:39], v[86:87], v[6:7]
	v_pk_fma_f32 v[8:9], v[38:39], v[102:103], v[8:9]
	v_pk_fma_f32 v[10:11], v[38:39], v[118:119], v[10:11]
	v_pk_fma_f32 v[12:13], v[38:39], v[134:135], v[12:13]
	v_pk_fma_f32 v[14:15], v[38:39], v[182:183], v[14:15]
	v_pk_fma_f32 v[144:145], v[38:39], v[198:199], v[144:145]
	v_pk_fma_f32 v[146:147], v[38:39], v[214:215], v[146:147]
	v_pk_fma_f32 v[148:149], v[38:39], v[230:231], v[148:149]
	v_pk_fma_f32 v[6:7], v[40:41], v[88:89], v[6:7]
	v_pk_fma_f32 v[8:9], v[40:41], v[104:105], v[8:9]
	v_pk_fma_f32 v[10:11], v[40:41], v[120:121], v[10:11]
	v_pk_fma_f32 v[12:13], v[40:41], v[136:137], v[12:13]
	v_pk_fma_f32 v[14:15], v[40:41], v[184:185], v[14:15]
	v_pk_fma_f32 v[144:145], v[40:41], v[200:201], v[144:145]
	v_pk_fma_f32 v[146:147], v[40:41], v[216:217], v[146:147]
	v_pk_fma_f32 v[148:149], v[40:41], v[232:233], v[148:149]
	v_pk_fma_f32 v[6:7], v[42:43], v[90:91], v[6:7]
	v_pk_fma_f32 v[8:9], v[42:43], v[106:107], v[8:9]
	v_pk_fma_f32 v[10:11], v[42:43], v[122:123], v[10:11]
	v_pk_fma_f32 v[12:13], v[42:43], v[138:139], v[12:13]
	v_pk_fma_f32 v[14:15], v[42:43], v[186:187], v[14:15]
	v_pk_fma_f32 v[144:145], v[42:43], v[202:203], v[144:145]
	v_pk_fma_f32 v[146:147], v[42:43], v[218:219], v[146:147]
	v_pk_fma_f32 v[148:149], v[42:43], v[234:235], v[148:149]
	v_pk_fma_f32 v[6:7], v[44:45], v[92:93], v[6:7]
	v_pk_fma_f32 v[8:9], v[44:45], v[108:109], v[8:9]
	v_pk_fma_f32 v[10:11], v[44:45], v[124:125], v[10:11]
	v_pk_fma_f32 v[12:13], v[44:45], v[140:141], v[12:13]
	v_pk_fma_f32 v[14:15], v[44:45], v[188:189], v[14:15]
	v_pk_fma_f32 v[144:145], v[44:45], v[204:205], v[144:145]
	v_pk_fma_f32 v[146:147], v[44:45], v[220:221], v[146:147]
	v_pk_fma_f32 v[148:149], v[44:45], v[236:237], v[148:149]
	v_pk_fma_f32 v[6:7], v[46:47], v[94:95], v[6:7]
	v_pk_fma_f32 v[8:9], v[46:47], v[110:111], v[8:9]
	v_pk_fma_f32 v[10:11], v[46:47], v[126:127], v[10:11]
	v_pk_fma_f32 v[12:13], v[46:47], v[142:143], v[12:13]
	v_pk_fma_f32 v[14:15], v[46:47], v[190:191], v[14:15]
	v_pk_fma_f32 v[144:145], v[46:47], v[206:207], v[144:145]
	v_pk_fma_f32 v[146:147], v[46:47], v[222:223], v[146:147]
	v_pk_fma_f32 v[148:149], v[46:47], v[238:239], v[148:149]
	v_add_f32_e32 v6, v6, v7
	v_add_f32_e32 v8, v8, v9
	v_add_f32_e32 v10, v10, v11
	v_add_f32_e32 v12, v12, v13
	v_add_f32_e32 v14, v14, v15
	v_add_f32_e32 v144, v144, v145
	v_add_f32_e32 v146, v146, v147
	v_add_f32_e32 v148, v148, v149
	s_nop 1
	v_permlane32_swap_b32_e32 v6, v14
	v_permlane32_swap_b32_e32 v8, v144
	v_permlane32_swap_b32_e32 v10, v146
	v_permlane32_swap_b32_e32 v12, v148
	v_add_f32_e32 v6, v6, v14
	v_add_f32_e32 v8, v8, v144
	v_add_f32_e32 v10, v10, v146
	v_add_f32_e32 v12, v12, v148
	s_nop 1
	v_add_f32_dpp v14, v6, v6 row_ror:8 row_mask:0xf bank_mask:0xf bound_ctrl:1
	v_add_f32_dpp v144, v8, v8 row_ror:8 row_mask:0xf bank_mask:0xf bound_ctrl:1
	v_add_f32_dpp v146, v10, v10 row_ror:8 row_mask:0xf bank_mask:0xf bound_ctrl:1
	v_add_f32_dpp v148, v12, v12 row_ror:8 row_mask:0xf bank_mask:0xf bound_ctrl:1
	v_cndmask_b32_e64 v6, v14, v144, s[64:65]
	v_cndmask_b32_e64 v8, v146, v148, s[64:65]
	s_nop 1
	v_add_f32_dpp v10, v6, v6 row_half_mirror row_mask:0xf bank_mask:0xf bound_ctrl:1
	v_add_f32_dpp v12, v8, v8 row_half_mirror row_mask:0xf bank_mask:0xf bound_ctrl:1
	v_cndmask_b32_e64 v6, v10, v12, s[66:67]
	s_nop 1
	v_add_f32_dpp v6, v6, v6 quad_perm:[1,0,3,2] row_mask:0xf bank_mask:0xf bound_ctrl:1
	s_nop 1
	v_add_f32_dpp v6, v6, v6 quad_perm:[2,3,0,1] row_mask:0xf bank_mask:0xf bound_ctrl:1
	s_nop 0
	ds_swizzle_b32 v254, v6 offset:0x401f
	s_waitcnt lgkmcnt(0)
	v_add_f32_e32 v248, v6, v254
	v_add_f32_e32 v248, v248, v156
	v_mul_f32_e64 v249, -|v248|, s57
	v_exp_f32_e32 v249, v249
	v_min_f32_e32 v253, 0, v248
	v_add_f32_e32 v250, 1.0, v249
	v_log_f32_e32 v251, v250
	v_add_f32_e32 v252, -1.0, v250
	v_rcp_f32_e32 v250, v252
	v_cmp_eq_f32_e32 vcc, 0, v252
	v_mul_f32_e32 v251, 0x3f317218, v251
	v_mul_f32_e32 v251, v251, v249
	v_mul_f32_e32 v251, v251, v250
	v_cndmask_b32_e32 v251, v251, v249, vcc
	v_sub_f32_e32 v253, v253, v251
	s_mov_b64 exec, s[62:63]
	global_store_dword v4, v253, s[26:27]
	s_mov_b64 exec, -1
	s_add_u32 s12, s12, s53
	s_addc_u32 s13, s13, 0
	s_add_u32 s14, s14, s54
	s_addc_u32 s15, s15, 0
	s_add_u32 s26, s26, s55
	s_addc_u32 s27, s27, 0
	s_add_i32 s0, s0, s96
	s_cmp_lt_i32 s0, 0x8000
	s_cbranch_scc0 .Lrow_done
	s_add_i32 s1, s0, s59
	s_min_i32 s1, s1, s61
	s_lshl_b32 s4, s1, 12
	s_add_u32 s4, s10, s4
	s_addc_u32 s5, s11, 0
	global_load_dwordx4 v[32:35], v1, s[4:5]
	global_load_dwordx4 v[36:39], v1, s[4:5] offset:1024
	global_load_dwordx4 v[40:43], v1, s[4:5] offset:2048
	global_load_dwordx4 v[44:47], v1, s[4:5] offset:3072
	s_waitcnt vmcnt(20)
	v_pk_mul_f32 v[150:151], v[48:49], v[48:49]
	v_pk_fma_f32 v[150:151], v[50:51], v[50:51], v[150:151]
	v_pk_fma_f32 v[150:151], v[52:53], v[52:53], v[150:151]
	v_pk_fma_f32 v[150:151], v[54:55], v[54:55], v[150:151]
	v_pk_fma_f32 v[150:151], v[56:57], v[56:57], v[150:151]
	v_pk_fma_f32 v[150:151], v[58:59], v[58:59], v[150:151]
	v_pk_fma_f32 v[150:151], v[60:61], v[60:61], v[150:151]
	v_pk_fma_f32 v[150:151], v[62:63], v[62:63], v[150:151]
	v_add_f32_e32 v150, v150, v151
	s_nop 1
	v_add_f32_dpp v150, v150, v150 quad_perm:[1,0,3,2] row_mask:0xf bank_mask:0xf bound_ctrl:1
	s_nop 1
	v_add_f32_dpp v150, v150, v150 quad_perm:[2,3,0,1] row_mask:0xf bank_mask:0xf bound_ctrl:1
	s_nop 1
	v_add_f32_dpp v150, v150, v150 row_half_mirror row_mask:0xf bank_mask:0xf bound_ctrl:1
	s_nop 1
	v_add_f32_dpp v150, v150, v150 row_mirror row_mask:0xf bank_mask:0xf bound_ctrl:1
	s_nop 1
	v_readlane_b32 s7, v150, 0
	v_readlane_b32 s8, v150, 16
	v_readlane_b32 s9, v150, 32
	v_readlane_b32 s18, v150, 48
	s_nop 1
	v_mov_b32_e32 v150, s7
	v_add_f32_e32 v150, s8, v150
	v_add_f32_e32 v150, s9, v150
	v_add_f32_e32 v150, s18, v150
	v_fmamk_f32 v150, v150, 0x3a800000, v153
	v_sqrt_f32_e32 v152, v150
	s_nop 0
	v_rcp_f32_e32 v154, v152
	s_mov_b64 exec, 1
	global_store_dword v0, v152, s[14:15]
	s_mov_b64 exec, -1
	v_pk_mul_f32 v[48:49], v[48:49], v[154:155] op_sel_hi:[1,0]
	v_pk_mul_f32 v[50:51], v[50:51], v[154:155] op_sel_hi:[1,0]
	v_pk_mul_f32 v[52:53], v[52:53], v[154:155] op_sel_hi:[1,0]
	v_pk_mul_f32 v[54:55], v[54:55], v[154:155] op_sel_hi:[1,0]
	v_pk_mul_f32 v[56:57], v[56:57], v[154:155] op_sel_hi:[1,0]
	v_pk_mul_f32 v[58:59], v[58:59], v[154:155] op_sel_hi:[1,0]
	v_pk_mul_f32 v[60:61], v[60:61], v[154:155] op_sel_hi:[1,0]
	v_pk_mul_f32 v[62:63], v[62:63], v[154:155] op_sel_hi:[1,0]
	v_pk_mul_f32 v[48:49], v[48:49], v[64:65]
	v_pk_mul_f32 v[50:51], v[50:51], v[66:67]
	v_pk_mul_f32 v[52:53], v[52:53], v[68:69]
	v_pk_mul_f32 v[54:55], v[54:55], v[70:71]
	v_pk_mul_f32 v[56:57], v[56:57], v[72:73]
	v_pk_mul_f32 v[58:59], v[58:59], v[74:75]
	v_pk_mul_f32 v[60:61], v[60:61], v[76:77]
	v_pk_mul_f32 v[62:63], v[62:63], v[78:79]
	v_cvt_pk_bf16_f32 v240, v48, v49
	v_cvt_pk_bf16_f32 v241, v50, v51
	v_cvt_pk_bf16_f32 v242, v52, v53
	v_cvt_pk_bf16_f32 v243, v54, v55
	v_cvt_pk_bf16_f32 v244, v56, v57
	v_cvt_pk_bf16_f32 v245, v58, v59
	v_cvt_pk_bf16_f32 v246, v60, v61
	v_cvt_pk_bf16_f32 v247, v62, v63
	global_store_dwordx2 v2, v[240:241], s[12:13]
	global_store_dwordx2 v2, v[242:243], s[12:13] offset:512
	global_store_dwordx2 v2, v[244:245], s[12:13] offset:1024
	global_store_dwordx2 v2, v[246:247], s[12:13] offset:1536
	v_pk_mul_f32 v[6:7], v[48:49], v[80:81]
	v_pk_mul_f32 v[8:9], v[48:49], v[96:97]
	v_pk_mul_f32 v[10:11], v[48:49], v[112:113]
	v_pk_mul_f32 v[12:13], v[48:49], v[128:129]
	v_pk_mul_f32 v[14:15], v[48:49], v[176:177]
	v_pk_mul_f32 v[144:145], v[48:49], v[192:193]
	v_pk_mul_f32 v[146:147], v[48:49], v[208:209]
	v_pk_mul_f32 v[148:149], v[48:49], v[224:225]
	v_pk_fma_f32 v[6:7], v[50:51], v[82:83], v[6:7]
	v_pk_fma_f32 v[8:9], v[50:51], v[98:99], v[8:9]
	v_pk_fma_f32 v[10:11], v[50:51], v[114:115], v[10:11]
	v_pk_fma_f32 v[12:13], v[50:51], v[130:131], v[12:13]
	v_pk_fma_f32 v[14:15], v[50:51], v[178:179], v[14:15]
	v_pk_fma_f32 v[144:145], v[50:51], v[194:195], v[144:145]
	v_pk_fma_f32 v[146:147], v[50:51], v[210:211], v[146:147]
	v_pk_fma_f32 v[148:149], v[50:51], v[226:227], v[148:149]
	v_pk_fma_f32 v[6:7], v[52:53], v[84:85], v[6:7]
	v_pk_fma_f32 v[8:9], v[52:53], v[100:101], v[8:9]
	v_pk_fma_f32 v[10:11], v[52:53], v[116:117], v[10:11]
	v_pk_fma_f32 v[12:13], v[52:53], v[132:133], v[12:13]
	v_pk_fma_f32 v[14:15], v[52:53], v[180:181], v[14:15]
	v_pk_fma_f32 v[144:145], v[52:53], v[196:197], v[144:145]
	v_pk_fma_f32 v[146:147], v[52:53], v[212:213], v[146:147]
	v_pk_fma_f32 v[148:149], v[52:53], v[228:229], v[148:149]
	v_pk_fma_f32 v[6:7], v[54:55], v[86:87], v[6:7]
	v_pk_fma_f32 v[8:9], v[54:55], v[102:103], v[8:9]
	v_pk_fma_f32 v[10:11], v[54:55], v[118:119], v[10:11]
	v_pk_fma_f32 v[12:13], v[54:55], v[134:135], v[12:13]
	v_pk_fma_f32 v[14:15], v[54:55], v[182:183], v[14:15]
	v_pk_fma_f32 v[144:145], v[54:55], v[198:199], v[144:145]
	v_pk_fma_f32 v[146:147], v[54:55], v[214:215], v[146:147]
	v_pk_fma_f32 v[148:149], v[54:55], v[230:231], v[148:149]
	v_pk_fma_f32 v[6:7], v[56:57], v[88:89], v[6:7]
	v_pk_fma_f32 v[8:9], v[56:57], v[104:105], v[8:9]
	v_pk_fma_f32 v[10:11], v[56:57], v[120:121], v[10:11]
	v_pk_fma_f32 v[12:13], v[56:57], v[136:137], v[12:13]
	v_pk_fma_f32 v[14:15], v[56:57], v[184:185], v[14:15]
	v_pk_fma_f32 v[144:145], v[56:57], v[200:201], v[144:145]
	v_pk_fma_f32 v[146:147], v[56:57], v[216:217], v[146:147]
	v_pk_fma_f32 v[148:149], v[56:57], v[232:233], v[148:149]
	v_pk_fma_f32 v[6:7], v[58:59], v[90:91], v[6:7]
	v_pk_fma_f32 v[8:9], v[58:59], v[106:107], v[8:9]
	v_pk_fma_f32 v[10:11], v[58:59], v[122:123], v[10:11]
	v_pk_fma_f32 v[12:13], v[58:59], v[138:139], v[12:13]
	v_pk_fma_f32 v[14:15], v[58:59], v[186:187], v[14:15]
	v_pk_fma_f32 v[144:145], v[58:59], v[202:203], v[144:145]
	v_pk_fma_f32 v[146:147], v[58:59], v[218:219], v[146:147]
	v_pk_fma_f32 v[148:149], v[58:59], v[234:235], v[148:149]
	v_pk_fma_f32 v[6:7], v[60:61], v[92:93], v[6:7]
	v_pk_fma_f32 v[8:9], v[60:61], v[108:109], v[8:9]
	v_pk_fma_f32 v[10:11], v[60:61], v[124:125], v[10:11]
	v_pk_fma_f32 v[12:13], v[60:61], v[140:141], v[12:13]
	v_pk_fma_f32 v[14:15], v[60:61], v[188:189], v[14:15]
	v_pk_fma_f32 v[144:145], v[60:61], v[204:205], v[144:145]
	v_pk_fma_f32 v[146:147], v[60:61], v[220:221], v[146:147]
	v_pk_fma_f32 v[148:149], v[60:61], v[236:237], v[148:149]
	v_pk_fma_f32 v[6:7], v[62:63], v[94:95], v[6:7]
	v_pk_fma_f32 v[8:9], v[62:63], v[110:111], v[8:9]
	v_pk_fma_f32 v[10:11], v[62:63], v[126:127], v[10:11]
	v_pk_fma_f32 v[12:13], v[62:63], v[142:143], v[12:13]
	v_pk_fma_f32 v[14:15], v[62:63], v[190:191], v[14:15]
	v_pk_fma_f32 v[144:145], v[62:63], v[206:207], v[144:145]
	v_pk_fma_f32 v[146:147], v[62:63], v[222:223], v[146:147]
	v_pk_fma_f32 v[148:149], v[62:63], v[238:239], v[148:149]
	v_add_f32_e32 v6, v6, v7
	v_add_f32_e32 v8, v8, v9
	v_add_f32_e32 v10, v10, v11
	v_add_f32_e32 v12, v12, v13
	v_add_f32_e32 v14, v14, v15
	v_add_f32_e32 v144, v144, v145
	v_add_f32_e32 v146, v146, v147
	v_add_f32_e32 v148, v148, v149
	s_nop 1
	v_permlane32_swap_b32_e32 v6, v14
	v_permlane32_swap_b32_e32 v8, v144
	v_permlane32_swap_b32_e32 v10, v146
	v_permlane32_swap_b32_e32 v12, v148
	v_add_f32_e32 v6, v6, v14
	v_add_f32_e32 v8, v8, v144
	v_add_f32_e32 v10, v10, v146
	v_add_f32_e32 v12, v12, v148
	s_nop 1
	v_add_f32_dpp v14, v6, v6 row_ror:8 row_mask:0xf bank_mask:0xf bound_ctrl:1
	v_add_f32_dpp v144, v8, v8 row_ror:8 row_mask:0xf bank_mask:0xf bound_ctrl:1
	v_add_f32_dpp v146, v10, v10 row_ror:8 row_mask:0xf bank_mask:0xf bound_ctrl:1
	v_add_f32_dpp v148, v12, v12 row_ror:8 row_mask:0xf bank_mask:0xf bound_ctrl:1
	v_cndmask_b32_e64 v6, v14, v144, s[64:65]
	v_cndmask_b32_e64 v8, v146, v148, s[64:65]
	s_nop 1
	v_add_f32_dpp v10, v6, v6 row_half_mirror row_mask:0xf bank_mask:0xf bound_ctrl:1
	v_add_f32_dpp v12, v8, v8 row_half_mirror row_mask:0xf bank_mask:0xf bound_ctrl:1
	v_cndmask_b32_e64 v6, v10, v12, s[66:67]
	s_nop 1
	v_add_f32_dpp v6, v6, v6 quad_perm:[1,0,3,2] row_mask:0xf bank_mask:0xf bound_ctrl:1
	s_nop 1
	v_add_f32_dpp v6, v6, v6 quad_perm:[2,3,0,1] row_mask:0xf bank_mask:0xf bound_ctrl:1
	s_nop 0
	ds_swizzle_b32 v254, v6 offset:0x401f
	s_waitcnt lgkmcnt(0)
	v_add_f32_e32 v248, v6, v254
	v_add_f32_e32 v248, v248, v156
	v_mul_f32_e64 v249, -|v248|, s57
	v_exp_f32_e32 v249, v249
	v_min_f32_e32 v253, 0, v248
	v_add_f32_e32 v250, 1.0, v249
	v_log_f32_e32 v251, v250
	v_add_f32_e32 v252, -1.0, v250
	v_rcp_f32_e32 v250, v252
	v_cmp_eq_f32_e32 vcc, 0, v252
	v_mul_f32_e32 v251, 0x3f317218, v251
	v_mul_f32_e32 v251, v251, v249
	v_mul_f32_e32 v251, v251, v250
	v_cndmask_b32_e32 v251, v251, v249, vcc
	v_sub_f32_e32 v253, v253, v251
	s_mov_b64 exec, s[62:63]
	global_store_dword v4, v253, s[26:27]
	s_mov_b64 exec, -1
	s_add_u32 s12, s12, s53
	s_addc_u32 s13, s13, 0
	s_add_u32 s14, s14, s54
	s_addc_u32 s15, s15, 0
	s_add_u32 s26, s26, s55
	s_addc_u32 s27, s27, 0
	s_add_i32 s0, s0, s96
	s_cmp_lt_i32 s0, 0x8000
	s_cbranch_scc1 .Lrow_loop
.Lrow_done:
.LBB0_295:
	s_waitcnt vmcnt(0)
	s_barrier
	s_mov_b64 s[0:1], exec
	v_readlane_b32 s4, v255, 21
	v_readlane_b32 s5, v255, 22
	s_and_b64 s[4:5], s[0:1], s[4:5]
	s_mov_b64 exec, s[4:5]
	s_cbranch_execz .LBB0_347
	s_add_i32 s3, 0, 0x20160
	v_mov_b32_e32 v0, s3
	s_waitcnt vmcnt(0) expcnt(0) lgkmcnt(0)
	ds_read_b32 v2, v0
	s_add_i32 s3, 0, 0x20164
	v_mov_b32_e32 v0, s3
	ds_read_b32 v0, v0
	s_waitcnt lgkmcnt(1)
	v_cmp_ne_u32_e32 vcc, 0, v2
	s_cbranch_vccnz .LBB0_311
	s_add_u32 s4, s30, 0x4a0200
	s_addc_u32 s5, s31, 0
	s_add_u32 s6, s30, 0x4a0400
	s_addc_u32 s7, s31, 0
	s_add_u32 s8, s30, 0x4a0500
	s_addc_u32 s9, s31, 0
	s_add_u32 s10, s30, 0x4a0600
	s_addc_u32 s11, s31, 0
	s_add_u32 s12, s30, 0x4a0700
	s_addc_u32 s13, s31, 0
	s_add_u32 s14, s30, 0x4a0800
	s_addc_u32 s15, s31, 0
	s_add_u32 s16, s30, 0x4a0900
	s_addc_u32 s17, s31, 0
	s_add_u32 s18, s30, 0x4a0a00
	s_addc_u32 s19, s31, 0
	s_add_u32 s20, s30, 0x4a0b00
	s_addc_u32 s21, s31, 0
	s_add_u32 s22, s30, 0x4a0c00
	s_addc_u32 s23, s31, 0
	s_add_u32 s24, s30, 0x4a0d00
	s_addc_u32 s25, s31, 0
	s_add_u32 s36, s30, 0x4a0e00
	s_addc_u32 s37, s31, 0
	s_add_u32 s38, s30, 0x4a0f00
	s_addc_u32 s39, s31, 0
	s_add_u32 s40, s30, 0x4a1000
	s_addc_u32 s41, s31, 0
	s_add_u32 s42, s30, 0x4a1100
	s_addc_u32 s43, s31, 0
	s_add_u32 s44, s30, 0x4a1200
	v_readlane_b32 s3, v255, 1
	s_addc_u32 s45, s31, 0
	s_mul_i32 s3, s85, s3
	s_add_u32 s50, s30, 0x4a1300
	s_mul_i32 s3, s3, s84
	s_addc_u32 s51, s31, 0
	s_mov_b32 s60, 1
	v_mov_b32_e32 v16, 0
	s_branch .LBB0_299
